# gate epilogue: PP rows of rounds 2-4 touched while round 1 loads (L2 prefetch) - on top of v63
# baseline (speedup 1.0000x reference)
.LBB0_2407:
	s_mov_b32 s7, -1
	s_mov_b32 s8, s26
	v_mbcnt_lo_u32_b32 v40, s7, 0
	v_mbcnt_hi_u32_b32 v40, s7, v40
	s_mov_b32 s7, s29
	v_and_b32_e32 v41, 15, v40
	v_ashrrev_i32_e32 v40, 4, v40
	s_lshl_b32 s3, s3, 8
	s_lshl_b32 s7, s7, 6
	s_lshl_b32 s0, s0, 12
	s_add_i32 s7, s7, s3
	s_lshl_b32 s2, s2, 8
	s_lshl_b32 s3, s8, 5
	s_and_b32 s0, s0, 0x1000
	s_add_i32 s3, s3, s2
	s_add_i32 s0, s0, 0
	s_lshl_b32 s2, s8, 7
	s_add_i32 s0, s0, s2
	v_add_u32_e32 v188, s7, v41
	v_lshl_add_u32 v186, v40, 3, s3
	v_lshl_add_u32 v40, v40, 5, s0
	v_add_u32_e32 v204, 0x22000, v40
	v_lshlrev_b32_e32 v40, 1, v188
	v_ashrrev_i32_e32 v41, 31, v40
	v_lshl_add_u64 v[40:41], v[40:41], 2, s[54:55]
	v_ashrrev_i32_e32 v189, 31, v188
	v_ashrrev_i32_e32 v187, 31, v186
	global_load_dwordx2 v[196:197], v[40:41], off
	v_lshlrev_b64 v[40:41], 11, v[188:189]
	v_lshl_add_u64 v[194:195], v[40:41], 0, v[186:187]
	v_lshlrev_b64 v[40:41], 1, v[194:195]
	v_lshl_add_u64 v[42:43], s[56:57], 0, v[40:41]
	global_load_dwordx4 v[84:87], v[42:43], off
	v_lshl_add_u64 v[40:41], s[58:59], 0, v[40:41]
	global_load_dwordx4 v[80:83], v[40:41], off
	global_load_dwordx4 v[172:175], v[42:43], off offset:256
	global_load_dwordx4 v[168:171], v[40:41], off offset:256
	s_mov_b32 s99, 0
	s_mov_b32 s98, 0x20000
	v_lshl_add_u64 v[206:207], v[40:41], 0, s[98:99]
	global_load_dword v208, v[206:207], off
	global_load_dword v208, v[206:207], off offset:256
	s_mov_b32 s98, 0x30000
	v_lshl_add_u64 v[206:207], v[40:41], 0, s[98:99]
	global_load_dword v208, v[206:207], off
	global_load_dword v208, v[206:207], off offset:256
	s_mov_b32 s98, 0x80000
	v_lshl_add_u64 v[206:207], v[40:41], 0, s[98:99]
	global_load_dword v208, v[206:207], off
	global_load_dword v208, v[206:207], off offset:256
	s_mov_b32 s98, 0x90000
	v_lshl_add_u64 v[206:207], v[40:41], 0, s[98:99]
	global_load_dword v208, v[206:207], off
	global_load_dword v208, v[206:207], off offset:256
	s_mov_b32 s98, 0xa0000
	v_lshl_add_u64 v[206:207], v[40:41], 0, s[98:99]
	global_load_dword v208, v[206:207], off
	global_load_dword v208, v[206:207], off offset:256
	s_mov_b32 s98, 0xb0000
	v_lshl_add_u64 v[206:207], v[40:41], 0, s[98:99]
	global_load_dword v208, v[206:207], off
	global_load_dword v208, v[206:207], off offset:256
	v_add_u32_e32 v40, 16, v188
	v_ashrrev_i32_e32 v41, 31, v40
	v_lshlrev_b32_e32 v42, 1, v40
	v_lshlrev_b64 v[40:41], 11, v[40:41]
	v_ashrrev_i32_e32 v43, 31, v42
	v_lshl_add_u64 v[190:191], v[40:41], 0, v[186:187]
	v_lshl_add_u64 v[42:43], v[42:43], 2, s[54:55]
	v_lshlrev_b64 v[40:41], 1, v[190:191]
	global_load_dwordx2 v[192:193], v[42:43], off
	v_lshl_add_u64 v[42:43], s[56:57], 0, v[40:41]
	v_lshl_add_u64 v[40:41], s[58:59], 0, v[40:41]
	global_load_dwordx4 v[164:167], v[42:43], off
	global_load_dwordx4 v[160:163], v[40:41], off
	global_load_dwordx4 v[156:159], v[42:43], off offset:256
	global_load_dwordx4 v[152:155], v[40:41], off offset:256
	v_mul_f32_e32 v78, 0xbfb8aa3b, v78
	v_mul_f32_e32 v79, 0xbfb8aa3b, v79
	v_exp_f32_e32 v78, v78
	v_exp_f32_e32 v79, v79
	v_mul_f32_e32 v76, 0xbfb8aa3b, v76
	v_mul_f32_e32 v77, 0xbfb8aa3b, v77
	v_exp_f32_e32 v76, v76
	v_exp_f32_e32 v77, v77
	ds_read_b128 v[48:51], v204
	ds_read_b128 v[40:43], v204 offset:16
	ds_read_b128 v[52:55], v204 offset:1024
	ds_read_b128 v[44:47], v204 offset:1040
	v_add_f32_e32 v78, 1.0, v78
	v_add_f32_e32 v79, 1.0, v79
	v_rcp_f32_e32 v78, v78
	v_rcp_f32_e32 v79, v79
	v_add_f32_e32 v76, 1.0, v76
	v_add_f32_e32 v77, 1.0, v77
	v_mul_f32_e32 v74, 0xbfb8aa3b, v74
	v_mul_f32_e32 v75, 0xbfb8aa3b, v75
	v_rcp_f32_e32 v76, v76
	v_rcp_f32_e32 v77, v77
	v_exp_f32_e32 v74, v74
	v_exp_f32_e32 v75, v75
	v_mul_f32_e32 v72, 0xbfb8aa3b, v72
	v_mul_f32_e32 v73, 0xbfb8aa3b, v73
	v_exp_f32_e32 v72, v72
	v_exp_f32_e32 v73, v73
	v_add_f32_e32 v74, 1.0, v74
	v_add_f32_e32 v75, 1.0, v75
	v_rcp_f32_e32 v74, v74
	v_rcp_f32_e32 v75, v75
	v_add_f32_e32 v72, 1.0, v72
	v_add_f32_e32 v73, 1.0, v73
	v_rcp_f32_e32 v72, v72
	v_rcp_f32_e32 v73, v73
	s_andn2_b64 vcc, exec, s[66:67]
	s_waitcnt vmcnt(0)
	v_cvt_f32_f16_e32 v200, v80
	v_cvt_f32_f16_e32 v198, v84
	v_cvt_f32_f16_sdwa v199, v84 dst_sel:DWORD dst_unused:UNUSED_PAD src0_sel:WORD_1
	v_cvt_f32_f16_e32 v84, v85
	v_cvt_f32_f16_sdwa v85, v85 dst_sel:DWORD dst_unused:UNUSED_PAD src0_sel:WORD_1
	v_cvt_f32_f16_sdwa v201, v80 dst_sel:DWORD dst_unused:UNUSED_PAD src0_sel:WORD_1
	v_cvt_f32_f16_e32 v80, v81
	v_cvt_f32_f16_sdwa v81, v81 dst_sel:DWORD dst_unused:UNUSED_PAD src0_sel:WORD_1
	v_pk_add_f32 v[84:85], v[84:85], v[196:197] op_sel_hi:[1,0] neg_lo:[0,1] neg_hi:[0,1]
	v_pk_add_f32 v[198:199], v[198:199], v[196:197] op_sel_hi:[1,0] neg_lo:[0,1] neg_hi:[0,1]
	v_pk_mul_f32 v[84:85], v[196:197], v[84:85] op_sel:[1,0]
	v_pk_mul_f32 v[198:199], v[196:197], v[198:199] op_sel:[1,0]
	s_waitcnt lgkmcnt(0)
	v_pk_fma_f32 v[84:85], v[84:85], v[50:51], v[54:55]
	v_pk_fma_f32 v[198:199], v[198:199], v[48:49], v[52:53]
	v_pk_fma_f32 v[78:79], v[78:79], v[80:81], v[84:85]
	v_cvt_f32_f16_e32 v80, v87
	v_cvt_f32_f16_sdwa v81, v87 dst_sel:DWORD dst_unused:UNUSED_PAD src0_sel:WORD_1
	v_pk_fma_f32 v[76:77], v[76:77], v[200:201], v[198:199]
	v_cvt_f32_f16_e32 v198, v86
	v_cvt_f32_f16_sdwa v199, v86 dst_sel:DWORD dst_unused:UNUSED_PAD src0_sel:WORD_1
	v_cvt_f32_f16_e32 v200, v82
	v_cvt_f32_f16_sdwa v201, v82 dst_sel:DWORD dst_unused:UNUSED_PAD src0_sel:WORD_1
	v_cvt_f32_f16_e32 v82, v83
	v_cvt_f32_f16_sdwa v83, v83 dst_sel:DWORD dst_unused:UNUSED_PAD src0_sel:WORD_1
	v_pk_add_f32 v[80:81], v[80:81], v[196:197] op_sel_hi:[1,0] neg_lo:[0,1] neg_hi:[0,1]
	v_pk_add_f32 v[198:199], v[198:199], v[196:197] op_sel_hi:[1,0] neg_lo:[0,1] neg_hi:[0,1]
	v_pk_mul_f32 v[80:81], v[196:197], v[80:81] op_sel:[1,0]
	v_pk_mul_f32 v[198:199], v[196:197], v[198:199] op_sel:[1,0]
	v_pk_fma_f32 v[80:81], v[80:81], v[42:43], v[46:47]
	v_pk_fma_f32 v[198:199], v[198:199], v[40:41], v[44:45]
	v_pk_fma_f32 v[74:75], v[74:75], v[82:83], v[80:81]
	v_cndmask_b32_e64 v80, 0, 1, s[66:67]
	v_cmp_ne_u32_e64 s[42:43], 1, v80
	v_cndmask_b32_e64 v80, 0, 1, s[68:69]
	v_pk_fma_f32 v[72:73], v[72:73], v[200:201], v[198:199]
	v_lshl_add_u64 v[198:199], v[194:195], 1, s[50:51]
	v_cmp_ne_u32_e64 s[40:41], 1, v80
	s_cbranch_vccnz .LBB0_2490
	v_cvt_pk_f16_f32 v80, v76, v77
	v_cvt_pk_f16_f32 v81, v78, v79
	v_cvt_pk_f16_f32 v82, v72, v73
	v_cvt_pk_f16_f32 v83, v74, v75
	s_and_b64 vcc, exec, s[40:41]
	global_store_dwordx4 v[198:199], v[80:83], off
	s_cbranch_vccnz .LBB0_2410
	s_nop 0
	v_cvt_pk_bf16_f32 v80, v76, v77
	v_cvt_pk_bf16_f32 v81, v78, v79
	v_cvt_pk_bf16_f32 v82, v72, v73
	v_cvt_pk_bf16_f32 v83, v74, v75
	v_lshl_add_u64 v[84:85], v[194:195], 1, s[48:49]
	global_store_dwordx4 v[84:85], v[80:83], off
